# attention: QK accumulators start from inline 0 / bias read straight into place (no v_mov), plus packed SwiGLU epilogue
# speedup vs baseline: 1.0139x; 1.0044x over previous
.LBB0_527:
	s_add_i32 s6, s10, s33
	s_add_i32 s6, s6, 1
	s_cmp_gt_i32 s6, -3
	s_cselect_b64 s[70:71], -1, 0
	s_mov_b64 s[74:75], -1
	s_and_b64 vcc, exec, s[70:71]
	s_cbranch_vccz .LBB0_529
	ds_read2_b32 v[82:83], v208 offset0:27 offset1:26
	ds_read2_b32 v[84:85], v208 offset0:25 offset1:24
	ds_read2_b32 v[86:87], v208 offset0:19 offset1:18
	ds_read2_b32 v[88:89], v208 offset0:17 offset1:16
	ds_read2_b32 v[90:91], v208 offset0:11 offset1:10
	ds_read2_b32 v[92:93], v208 offset0:9 offset1:8
	ds_read2_b32 v[94:95], v208 offset0:3 offset1:2
	ds_read2_b32 v[96:97], v208 offset0:1 offset1:0
	ds_read2_b32 v[98:99], v208 offset0:59 offset1:58
	ds_read2_b32 v[100:101], v208 offset0:57 offset1:56
	ds_read2_b32 v[102:103], v208 offset0:51 offset1:50
	ds_read2_b32 v[104:105], v208 offset0:49 offset1:48
	ds_read2_b32 v[106:107], v208 offset0:43 offset1:42
	ds_read2_b32 v[108:109], v208 offset0:41 offset1:40
	ds_read2_b32 v[110:111], v208 offset0:35 offset1:34
	ds_read2_b32 v[112:113], v208 offset0:33 offset1:32
	s_mov_b64 s[74:75], 0
.LBB0_529:
	s_andn2_b64 vcc, exec, s[74:75]
	v_mov_b32_e32 v186, 0
	s_cbranch_vccnz .LBB0_531
	s_add_i32 s6, s5, 0
	s_add_i32 s6, s6, 0x20400
	v_mov_b32_e32 v16, s6
	ds_read_b32 v186, v16
	v_mfma_f32_32x32x16_bf16 v[98:113], v[150:153], v[114:117], 0
	v_mbcnt_hi_u32_b32 v210, -1, v1
	v_xor_b32_e32 v209, 32, v210
	v_mfma_f32_32x32x16_bf16 v[82:97], v[4:7], v[114:117], 0
	v_mfma_f32_32x32x16_bf16 v[98:113], v[154:157], v[118:121], v[98:113]
	v_mfma_f32_32x32x16_bf16 v[82:97], v[8:11], v[118:121], v[82:97]
	v_mfma_f32_32x32x16_bf16 v[98:113], v[158:161], v[122:125], v[98:113]
	v_mfma_f32_32x32x16_bf16 v[82:97], v[12:15], v[122:125], v[82:97]
	v_mfma_f32_32x32x16_bf16 v[98:113], v[162:165], v[126:129], v[98:113]
	v_mfma_f32_32x32x16_bf16 v[82:97], v[146:149], v[126:129], v[82:97]
	s_branch .Lattn_q0_join
.LBB0_531:
	s_waitcnt lgkmcnt(0)
	v_mfma_f32_32x32x16_bf16 v[98:113], v[150:153], v[114:117], v[98:113]
	v_mbcnt_hi_u32_b32 v210, -1, v1
	v_xor_b32_e32 v209, 32, v210
	v_mfma_f32_32x32x16_bf16 v[82:97], v[4:7], v[114:117], v[82:97]
	v_mfma_f32_32x32x16_bf16 v[98:113], v[154:157], v[118:121], v[98:113]
	v_mfma_f32_32x32x16_bf16 v[82:97], v[8:11], v[118:121], v[82:97]
	v_mfma_f32_32x32x16_bf16 v[98:113], v[158:161], v[122:125], v[98:113]
	v_mfma_f32_32x32x16_bf16 v[82:97], v[12:15], v[122:125], v[82:97]
	v_mfma_f32_32x32x16_bf16 v[98:113], v[162:165], v[126:129], v[98:113]
	v_mfma_f32_32x32x16_bf16 v[82:97], v[146:149], v[126:129], v[82:97]
	.Lattn_q0_join:
	s_nop 15
	s_nop 7
	s_nop 0
	v_max3_f32 v16, v98, v99, v100
	v_max3_f32 v166, v82, v83, v84
	s_nop 0
	v_max3_f32 v16, v16, v101, v102
	v_max3_f32 v166, v166, v85, v86
	s_nop 0
	v_max3_f32 v16, v16, v103, v104
	v_max3_f32 v166, v166, v87, v88
	s_nop 0
	v_max3_f32 v16, v16, v105, v106
	v_max3_f32 v166, v166, v89, v90
	s_nop 0
	v_max3_f32 v16, v16, v107, v108
	v_max3_f32 v166, v166, v91, v92
	s_nop 0
	v_max3_f32 v16, v16, v109, v110
	v_max3_f32 v166, v166, v93, v94
	s_nop 0
	v_max3_f32 v16, v16, v111, v112
	v_max3_f32 v166, v166, v95, v96
	s_nop 0
	v_max3_f32 v16, v16, v166, v113
	v_and_b32_e32 v166, 64, v210
	v_add_u32_e32 v211, 64, v166
	v_cmp_lt_i32_e32 vcc, v209, v211
	v_max3_f32 v16, v16, v97, v16
	s_nop 1
	v_cndmask_b32_e32 v166, v210, v209, vcc
	v_lshlrev_b32_e32 v212, 2, v166
	ds_bpermute_b32 v166, v212, v16
	s_waitcnt lgkmcnt(0)
	v_max3_f32 v166, v16, v166, v16
	s_nop 0
	v_pk_add_f32 v[188:189], v[186:187], v[166:167]
	s_nop 0
	v_cmp_gt_f32_e32 vcc, v188, v189
	s_cbranch_vccz .LBB0_533
	s_nop 0
	v_cndmask_b32_e32 v166, v187, v188, vcc
	v_sub_f32_e32 v16, v187, v166
	v_exp_f32_e32 v16, v16
	v_mov_b32_e32 v187, v166
	v_mul_f32_e32 v207, v207, v16
	v_pk_mul_f32 v[80:81], v[80:81], v[16:17] op_sel_hi:[1,0]
	v_pk_mul_f32 v[78:79], v[78:79], v[16:17] op_sel_hi:[1,0]
	v_pk_mul_f32 v[76:77], v[76:77], v[16:17] op_sel_hi:[1,0]
	v_pk_mul_f32 v[74:75], v[74:75], v[16:17] op_sel_hi:[1,0]
	v_pk_mul_f32 v[72:73], v[72:73], v[16:17] op_sel_hi:[1,0]
	v_pk_mul_f32 v[70:71], v[70:71], v[16:17] op_sel_hi:[1,0]
	v_pk_mul_f32 v[68:69], v[68:69], v[16:17] op_sel_hi:[1,0]
	v_pk_mul_f32 v[66:67], v[66:67], v[16:17] op_sel_hi:[1,0]
	v_pk_mul_f32 v[64:65], v[64:65], v[16:17] op_sel_hi:[1,0]
	v_pk_mul_f32 v[62:63], v[62:63], v[16:17] op_sel_hi:[1,0]
	v_pk_mul_f32 v[60:61], v[60:61], v[16:17] op_sel_hi:[1,0]
	v_pk_mul_f32 v[58:59], v[58:59], v[16:17] op_sel_hi:[1,0]
	v_pk_mul_f32 v[56:57], v[56:57], v[16:17] op_sel_hi:[1,0]
	v_pk_mul_f32 v[54:55], v[54:55], v[16:17] op_sel_hi:[1,0]
	v_pk_mul_f32 v[52:53], v[52:53], v[16:17] op_sel_hi:[1,0]
	v_pk_mul_f32 v[50:51], v[50:51], v[16:17] op_sel_hi:[1,0]

.LBB0_537:
	ds_read_b64_tr_b16 v[98:99], v200 offset:0
	ds_read_b64_tr_b16 v[100:101], v200 offset:1024
	ds_read_b64_tr_b16 v[102:103], v200 offset:2048
	ds_read_b64_tr_b16 v[104:105], v200 offset:3072
	ds_read_b64_tr_b16 v[106:107], v200 offset:4096
	ds_read_b64_tr_b16 v[108:109], v200 offset:5120
	ds_read_b64_tr_b16 v[110:111], v200 offset:6144
	ds_read_b64_tr_b16 v[112:113], v200 offset:7168
	ds_read_b64_tr_b16 v[242:243], v201 offset:0
	ds_read_b64_tr_b16 v[244:245], v201 offset:1024
	ds_read_b64_tr_b16 v[246:247], v201 offset:2048
	ds_read_b64_tr_b16 v[248:249], v201 offset:3072
	ds_read_b64_tr_b16 v[250:251], v201 offset:4096
	ds_read_b64_tr_b16 v[252:253], v201 offset:5120
	ds_read_b64_tr_b16 v[168:169], v201 offset:6144
	ds_read_b64_tr_b16 v[170:171], v201 offset:7168
	s_mov_b64 s[74:75], -1
	s_waitcnt lgkmcnt(0)
	s_andn2_b64 vcc, exec, s[70:71]
	v_mfma_f32_32x32x16_bf16 v[66:81], v[98:101], v[94:97], v[66:81]
	v_mfma_f32_32x32x16_bf16 v[50:65], v[242:245], v[94:97], v[50:65]
	v_mfma_f32_32x32x16_bf16 v[66:81], v[102:105], v[90:93], v[66:81]
	v_mfma_f32_32x32x16_bf16 v[50:65], v[246:249], v[90:93], v[50:65]
	v_mfma_f32_32x32x16_bf16 v[66:81], v[106:109], v[86:89], v[66:81]
	v_mfma_f32_32x32x16_bf16 v[50:65], v[250:253], v[86:89], v[50:65]
	v_mfma_f32_32x32x16_bf16 v[66:81], v[110:113], v[82:85], v[66:81]
	v_mfma_f32_32x32x16_bf16 v[50:65], v[168:171], v[82:85], v[50:65]
	s_cbranch_vccnz .LBB0_539
	ds_read2_b32 v[82:83], v208 offset0:59 offset1:58
	ds_read2_b32 v[84:85], v208 offset0:57 offset1:56
	ds_read2_b32 v[86:87], v208 offset0:51 offset1:50
	ds_read2_b32 v[88:89], v208 offset0:49 offset1:48
	ds_read2_b32 v[90:91], v208 offset0:43 offset1:42
	ds_read2_b32 v[92:93], v208 offset0:41 offset1:40
	ds_read2_b32 v[94:95], v208 offset0:35 offset1:34
	ds_read2_b32 v[96:97], v208 offset0:33 offset1:32
	ds_read2_b32 v[98:99], v208 offset0:91 offset1:90
	ds_read2_b32 v[100:101], v208 offset0:89 offset1:88
	ds_read2_b32 v[102:103], v208 offset0:83 offset1:82
	ds_read2_b32 v[104:105], v208 offset0:81 offset1:80
	ds_read2_b32 v[106:107], v208 offset0:75 offset1:74
	ds_read2_b32 v[108:109], v208 offset0:73 offset1:72
	ds_read2_b32 v[110:111], v208 offset0:67 offset1:66
	ds_read2_b32 v[112:113], v208 offset0:65 offset1:64
	s_mov_b64 s[74:75], 0
	s_waitcnt lgkmcnt(0)
.LBB0_539:
	s_andn2_b64 vcc, exec, s[74:75]
	v_mov_b32_e32 v16, 0
	s_cbranch_vccnz .LBB0_541
	s_add_i32 s6, s5, 0
	s_add_i32 s6, s6, 0x20400
	v_mov_b32_e32 v16, s6
	ds_read_b32 v16, v16
	v_mfma_f32_32x32x16_bf16 v[98:113], v[150:153], v[130:133], 0
	s_nop 0
	v_mfma_f32_32x32x16_bf16 v[82:97], v[4:7], v[130:133], 0
	v_mfma_f32_32x32x16_bf16 v[98:113], v[154:157], v[134:137], v[98:113]
	v_mfma_f32_32x32x16_bf16 v[82:97], v[8:11], v[134:137], v[82:97]
	v_mfma_f32_32x32x16_bf16 v[98:113], v[158:161], v[138:141], v[98:113]
	v_mfma_f32_32x32x16_bf16 v[82:97], v[12:15], v[138:141], v[82:97]
	v_mfma_f32_32x32x16_bf16 v[98:113], v[162:165], v[142:145], v[98:113]
	v_mfma_f32_32x32x16_bf16 v[82:97], v[146:149], v[142:145], v[82:97]
	s_branch .Lattn_q1_join
.LBB0_541:
	v_mfma_f32_32x32x16_bf16 v[98:113], v[150:153], v[130:133], v[98:113]
	s_nop 0
	v_mfma_f32_32x32x16_bf16 v[82:97], v[4:7], v[130:133], v[82:97]
	v_mfma_f32_32x32x16_bf16 v[98:113], v[154:157], v[134:137], v[98:113]
	v_mfma_f32_32x32x16_bf16 v[82:97], v[8:11], v[134:137], v[82:97]
	v_mfma_f32_32x32x16_bf16 v[98:113], v[158:161], v[138:141], v[98:113]
	v_mfma_f32_32x32x16_bf16 v[82:97], v[12:15], v[138:141], v[82:97]
	v_mfma_f32_32x32x16_bf16 v[98:113], v[162:165], v[142:145], v[98:113]
	v_mfma_f32_32x32x16_bf16 v[82:97], v[146:149], v[142:145], v[82:97]
	.Lattn_q1_join:
	s_nop 15
	s_nop 7
	s_nop 0
	v_max3_f32 v4, v98, v99, v100
	v_max3_f32 v5, v82, v83, v84
	s_nop 0
	v_max3_f32 v4, v4, v101, v102
	v_max3_f32 v5, v5, v85, v86
	s_nop 0
	v_max3_f32 v4, v4, v103, v104
	v_max3_f32 v5, v5, v87, v88
	s_nop 0
	v_max3_f32 v4, v4, v105, v106
	v_max3_f32 v5, v5, v89, v90
	s_nop 0
	v_max3_f32 v4, v4, v107, v108
	v_max3_f32 v5, v5, v91, v92
	s_nop 0
	v_max3_f32 v4, v4, v109, v110
	v_max3_f32 v5, v5, v93, v94
	s_nop 0
	v_max3_f32 v4, v4, v111, v112
	v_max3_f32 v5, v5, v95, v96
	s_nop 0
	v_max3_f32 v4, v4, v5, v113
	s_nop 0
	v_max3_f32 v4, v4, v97, v4
	ds_bpermute_b32 v5, v212, v4
	s_waitcnt lgkmcnt(0)
	v_max3_f32 v166, v4, v5, v4
	s_nop 0
	v_pk_add_f32 v[4:5], v[16:17], v[166:167]
	s_nop 0
	v_cmp_gt_f32_e32 vcc, v4, v5
	s_cbranch_vccz .LBB0_543
	s_nop 0
	v_cndmask_b32_e32 v5, v17, v4, vcc
	v_sub_f32_e32 v4, v17, v5
	v_exp_f32_e32 v4, v4
	v_mov_b32_e32 v17, v5
	v_mul_f32_e32 v2, v2, v4
	v_pk_mul_f32 v[48:49], v[48:49], v[4:5] op_sel_hi:[1,0]
	v_pk_mul_f32 v[46:47], v[46:47], v[4:5] op_sel_hi:[1,0]
	v_pk_mul_f32 v[44:45], v[44:45], v[4:5] op_sel_hi:[1,0]
	v_pk_mul_f32 v[42:43], v[42:43], v[4:5] op_sel_hi:[1,0]
	v_pk_mul_f32 v[40:41], v[40:41], v[4:5] op_sel_hi:[1,0]
	v_pk_mul_f32 v[38:39], v[38:39], v[4:5] op_sel_hi:[1,0]
	v_pk_mul_f32 v[36:37], v[36:37], v[4:5] op_sel_hi:[1,0]
	v_pk_mul_f32 v[34:35], v[34:35], v[4:5] op_sel_hi:[1,0]
	v_pk_mul_f32 v[32:33], v[32:33], v[4:5] op_sel_hi:[1,0]
	v_pk_mul_f32 v[30:31], v[30:31], v[4:5] op_sel_hi:[1,0]
	v_pk_mul_f32 v[28:29], v[28:29], v[4:5] op_sel_hi:[1,0]
	v_pk_mul_f32 v[26:27], v[26:27], v[4:5] op_sel_hi:[1,0]
	v_pk_mul_f32 v[24:25], v[24:25], v[4:5] op_sel_hi:[1,0]
	v_pk_mul_f32 v[22:23], v[22:23], v[4:5] op_sel_hi:[1,0]
	v_pk_mul_f32 v[20:21], v[20:21], v[4:5] op_sel_hi:[1,0]
	v_pk_mul_f32 v[18:19], v[18:19], v[4:5] op_sel_hi:[1,0]
